# weight-conversion shadow work re-split: the quarter-unit workgroups (done early) take 80 of the 704 item pairs, workgroups 48..255 three rounds each
# baseline (speedup 1.0000x reference)
.LBB0_6:
	s_load_dwordx2 s[18:19], s[0:1], 0xc0
	s_lshl_b32 s2, s93, 3
	v_writelane_b32 v252, s2, 4
	s_load_dwordx16 s[60:75], s[0:1], 0x40
	v_mov_b32_e32 v203, 0x358637bd
	s_waitcnt lgkmcnt(0)
	s_lshl_b32 s33, s18, 3
	s_add_u32 s2, s8, 0x6204000
	s_addc_u32 s3, s9, 0
	v_writelane_b32 v252, s2, 5
	s_lshl_b32 s96, s18, 5
	v_mov_b32_e32 v204, 0x3c0881c4
	v_writelane_b32 v252, s3, 6
	v_writelane_b32 v252, s20, 7
	v_mov_b32_e32 v205, 0xbab64f3b
	v_mov_b32_e32 v206, 1
	v_writelane_b32 v252, s21, 8
	s_lshl_b32 s20, s93, 1
	s_cmpk_lt_i32 s20, 0x2180
	s_cselect_b64 s[2:3], -1, 0
	v_writelane_b32 v252, s2, 9
	v_mov_b32_e32 v215, 0x4000
	v_bfrev_b32_e32 v216, 0.5
	v_writelane_b32 v252, s3, 10
	s_add_u32 s2, s8, 0x16a94000
	s_addc_u32 s3, s9, 0
	s_add_u32 s46, s8, 0x4000
	v_writelane_b32 v252, s2, 11
	s_addc_u32 s47, s9, 0
	v_mov_b32_e32 v217, 0x3e000000
	v_writelane_b32 v252, s3, 12
	s_add_u32 s2, s8, 0x1304000
	s_addc_u32 s3, s9, 0
	v_writelane_b32 v252, s2, 13
	v_mov_b32_e32 v218, 0x4f
	v_mov_b32_e32 v219, 0x5f
	v_writelane_b32 v252, s3, 14
	s_add_u32 s2, s8, 0x804000
	s_addc_u32 s3, s9, 0
	v_writelane_b32 v252, s2, 15
	v_mov_b32_e32 v220, 0x6f
	v_mov_b32_e32 v221, 0xfffff500
	v_writelane_b32 v252, s3, 16
	s_add_u32 s2, s8, 0x604000
	s_addc_u32 s3, s9, 0
	s_lshl_b32 s48, s18, 1
	v_writelane_b32 v252, s2, 17
	s_add_u32 s44, s8, 0x16ac4000
	s_addc_u32 s45, s9, 0
	v_writelane_b32 v252, s3, 18
	s_lshl_b32 s2, s93, 9
	s_lshl_b32 s56, s18, 9
	v_writelane_b32 v252, s2, 19
	s_add_u32 s2, s8, 0xa304000
	s_addc_u32 s3, s9, 0
	v_writelane_b32 v252, s2, 20
	s_cmpk_lt_i32 s93, 0x100
	v_mov_b32_e32 v222, 0x7f800000
	v_writelane_b32 v252, s3, 21
	s_cselect_b64 s[2:3], -1, 0
	v_writelane_b32 v252, s2, 22
	v_not_b32_e32 v223, 63
	v_not_b32_e32 v224, 31
	v_writelane_b32 v252, s3, 23
	s_and_b32 s2, s93, 3
	v_writelane_b32 v252, s2, 24
	s_lshl_b32 s2, s93, 6
	s_and_b32 s2, s2, 0x3f00
	v_writelane_b32 v252, s2, 25
	s_ashr_i32 s2, s93, 31
	v_writelane_b32 v252, s2, 26
	s_lshr_b32 s2, s2, 29
	s_add_i32 s2, s93, s2
	s_ashr_i32 s21, s2, 3
	s_and_b32 s2, s2, -8
	s_sub_i32 s22, s93, s2
	s_lshl_b32 s3, s22, 5
	s_ashr_i32 s2, s18, 31
	s_add_u32 s12, s8, 0xc404000
	v_writelane_b32 v252, s2, 27
	s_addc_u32 s13, s9, 0
	v_writelane_b32 v252, s12, 28
	s_mul_hi_i32 s2, s93, 0x2aaaaaab
	v_mov_b32_e32 v225, 0x7fc00000
	v_writelane_b32 v252, s13, 29
	s_add_u32 s12, s8, 0x16acc000
	s_addc_u32 s13, s9, 0
	v_writelane_b32 v252, s12, 30
	s_movk_i32 s37, 0x4000
	s_mov_b32 s30, 0x18000
	v_writelane_b32 v252, s13, 31
	s_add_u32 s12, s8, 0x12da4000
	s_addc_u32 s13, s9, 0
	s_add_u32 s24, s8, 0x139d4000
	s_addc_u32 s25, s9, 0
	v_writelane_b32 v252, s12, 32
	s_add_u32 s94, s8, 0x15234000
	s_addc_u32 s95, s9, 0
	v_writelane_b32 v252, s13, 33
	s_lshr_b32 s12, s2, 31
	s_add_i32 s15, s2, s12
	s_mul_i32 s2, s15, 6
	s_sub_i32 s23, s93, s2
	s_lshl_b32 s16, s15, 8
	s_lshl_b32 s26, s23, 6
	s_add_i32 s2, s16, 0x100
	s_ashr_i32 s27, s26, 31
	s_cmpk_lt_i32 s93, 0x60
	s_cselect_b64 s[28:29], -1, 0
	v_writelane_b32 v252, s28, 34
	s_lshl_b32 s13, s15, 4
	s_addk_i32 s13, 0x4000
	v_writelane_b32 v252, s29, 35
	v_writelane_b32 v252, s13, 36
	s_sub_i32 s13, s18, s23
	s_add_i32 s13, s13, 5
	s_lshl_b64 s[28:29], s[26:27], 1
	v_writelane_b32 v252, s13, 37
	s_add_u32 s13, s8, s28
	v_writelane_b32 v252, s28, 38
	s_addc_u32 s17, s9, s29
	s_mul_i32 s12, s23, 0x208000
	v_writelane_b32 v252, s29, 39
	s_add_u32 s28, s13, 0xc404500
	s_addc_u32 s29, s17, 0
	v_writelane_b32 v252, s28, 40
	s_add_u32 s12, s8, s12
	s_mov_b32 s31, 0xc000
	v_writelane_b32 v252, s29, 41
	v_writelane_b32 v252, s26, 42
	s_mul_hi_i32 s13, s26, 0x8200
	s_addc_u32 s13, s9, s13
	s_add_u32 s12, s12, 0x12174000
	v_writelane_b32 v252, s27, 43
	s_addc_u32 s13, s13, 0
	v_writelane_b32 v252, s12, 44
	s_mov_b32 s36, 0x30000
	s_movk_i32 s57, 0x1700
	v_writelane_b32 v252, s13, 45
	s_ashr_i32 s12, s23, 31
	v_writelane_b32 v252, s12, 46
	s_cmpk_lt_i32 s93, 0x30c
	s_mul_i32 s12, s22, 0x61
	s_cselect_b64 s[26:27], -1, 0
	s_add_i32 s17, s12, 4
	v_writelane_b32 v252, s26, 47
	s_add_u32 s12, s8, 0x16ac8000
	s_addc_u32 s13, s9, 0
	v_writelane_b32 v252, s27, 48
	v_writelane_b32 v252, s12, 49
	s_movk_i32 s76, 0x104
	s_mov_b32 s77, 0x5c000
	v_writelane_b32 v252, s13, 50
	s_add_u32 s12, s8, 0x14604000
	s_addc_u32 s13, s9, 0
	v_writelane_b32 v252, s12, 51
	s_nop 1
	v_writelane_b32 v252, s13, 52
	s_mul_i32 s12, s18, -3
	s_addk_i32 s12, 0x30c
	s_cmp_eq_u32 s18, 0x100
	s_cselect_b32 s12, 48, s12
	s_cmp_gt_i32 s12, 0
	s_cselect_b64 s[26:27], -1, 0
	s_cmp_le_i32 s18, s12
	s_cselect_b64 s[28:29], -1, 0
	v_writelane_b32 v252, s28, 53
	s_cmp_lt_i32 s93, s12
	s_nop 0
	v_writelane_b32 v252, s29, 54
	s_cselect_b64 s[28:29], -1, 0
	s_sub_i32 s13, s93, s12
	v_writelane_b32 v252, s28, 55
	s_cmpk_lt_u32 s13, 0x2c0
	s_nop 0
	v_writelane_b32 v252, s29, 56
	s_cselect_b64 s[28:29], -1, 0
	v_writelane_b32 v252, s28, 57
	s_sub_i32 s13, s18, s12
	s_lshl_b32 s13, s13, 1
	v_writelane_b32 v252, s29, 58
	v_writelane_b32 v252, s13, 59
	s_cmp_gt_i32 s18, s12
	s_cselect_b64 s[12:13], -1, 0
	v_writelane_b32 v252, s26, 60
	s_and_b64 s[12:13], s[26:27], s[12:13]
	s_cmpk_lt_i32 s93, 0x2c0
	v_writelane_b32 v252, s27, 61
	v_writelane_b32 v252, s12, 62
	s_mov_b32 s28, 0x800000
	s_movk_i32 s29, 0x6000
	v_writelane_b32 v252, s13, 63
	s_cselect_b64 s[12:13], -1, 0
	v_writelane_b32 v253, s12, 0
	s_cmp_gt_i32 s11, 38
	s_nop 0
	v_writelane_b32 v253, s13, 1
	s_cselect_b64 s[12:13], -1, 0
	v_writelane_b32 v253, s12, 2
	s_nop 1
	v_writelane_b32 v253, s13, 3
	s_add_u32 s12, s8, 0x200
	s_addc_u32 s13, s9, 0
	v_writelane_b32 v253, s12, 4
	s_nop 1
	v_writelane_b32 v253, s13, 5
	s_add_u32 s12, s8, 0x1000
	s_addc_u32 s13, s9, 0
	v_writelane_b32 v253, s12, 6
	s_nop 1
	v_writelane_b32 v253, s13, 7
	s_add_u32 s12, s8, 0x1100
	s_addc_u32 s13, s9, 0
	v_writelane_b32 v253, s12, 8
	s_nop 1
	v_writelane_b32 v253, s13, 9
	s_add_u32 s12, s8, 0x1200
	s_addc_u32 s13, s9, 0
	v_writelane_b32 v253, s12, 10
	s_nop 1
	v_writelane_b32 v253, s13, 11
	s_add_u32 s12, s8, 0x1300
	s_addc_u32 s13, s9, 0
	v_writelane_b32 v253, s12, 12
	s_cmp_eq_u32 s14, 15
	s_nop 0
	v_writelane_b32 v253, s13, 13
	s_cselect_b64 s[12:13], -1, 0
	v_writelane_b32 v253, s12, 14
	s_cmp_eq_u32 s14, 14
	s_nop 0
	v_writelane_b32 v253, s13, 15
	s_cselect_b64 s[12:13], -1, 0
	v_writelane_b32 v253, s12, 16
	s_cmp_eq_u32 s14, 13
	s_nop 0
	v_writelane_b32 v253, s13, 17
	s_cselect_b64 s[12:13], -1, 0
	v_writelane_b32 v253, s12, 18
	s_cmp_eq_u32 s14, 12
	s_nop 0
	v_writelane_b32 v253, s13, 19
	s_cselect_b64 s[12:13], -1, 0
	v_writelane_b32 v253, s12, 20
	s_cmp_eq_u32 s14, 11
	s_nop 0
	v_writelane_b32 v253, s13, 21
	s_cselect_b64 s[12:13], -1, 0
	v_writelane_b32 v253, s12, 22
	s_cmp_eq_u32 s14, 10
	s_nop 0
	v_writelane_b32 v253, s13, 23
	s_cselect_b64 s[12:13], -1, 0
	v_writelane_b32 v253, s12, 24
	s_cmp_eq_u32 s14, 9
	s_nop 0
	v_writelane_b32 v253, s13, 25
	s_cselect_b64 s[12:13], -1, 0
	v_writelane_b32 v253, s12, 26
	s_cmp_eq_u32 s14, 8
	s_nop 0
	v_writelane_b32 v253, s13, 27
	s_cselect_b64 s[12:13], -1, 0
	v_writelane_b32 v253, s12, 28
	s_cmp_eq_u32 s14, 7
	s_nop 0
	v_writelane_b32 v253, s13, 29
	s_cselect_b64 s[12:13], -1, 0
	v_writelane_b32 v253, s12, 30
	s_cmp_eq_u32 s14, 6
	s_nop 0
	v_writelane_b32 v253, s13, 31
	s_cselect_b64 s[12:13], -1, 0
	v_writelane_b32 v253, s12, 32
	s_cmp_eq_u32 s14, 5
	s_nop 0
	v_writelane_b32 v253, s13, 33
	s_cselect_b64 s[12:13], -1, 0
	v_writelane_b32 v253, s12, 34
	s_cmp_eq_u32 s14, 4
	s_nop 0
	v_writelane_b32 v253, s13, 35
	s_cselect_b64 s[12:13], -1, 0
	v_writelane_b32 v253, s12, 36
	s_cmp_eq_u32 s14, 3
	s_nop 0
	v_writelane_b32 v253, s13, 37
	s_cselect_b64 s[12:13], -1, 0
	v_writelane_b32 v253, s12, 38
	s_cmp_eq_u32 s14, 2
	s_nop 0
	v_writelane_b32 v253, s13, 39
	s_cselect_b64 s[12:13], -1, 0
	v_writelane_b32 v253, s12, 40
	s_cmp_eq_u32 s14, 1
	s_nop 0
	v_writelane_b32 v253, s13, 41
	s_cselect_b64 s[12:13], -1, 0
	v_writelane_b32 v253, s12, 42
	s_cmp_eq_u32 s14, 0
	s_nop 0
	v_writelane_b32 v253, s13, 43
	s_cselect_b64 s[12:13], -1, 0
	v_writelane_b32 v253, s12, 44
	s_nop 1
	v_writelane_b32 v253, s13, 45
	s_lshl_b32 s12, s14, 8
	s_add_u32 s12, s8, s12
	s_addc_u32 s13, s9, 0
	s_add_u32 s26, s12, 0x1400
	s_addc_u32 s27, s13, 0
	v_writelane_b32 v253, s26, 46
	s_add_u32 s12, s12, 0x2400
	s_addc_u32 s13, s13, 0
	v_writelane_b32 v253, s27, 47
	v_writelane_b32 v253, s12, 48
	s_mov_b64 s[26:27], 0x400
	s_nop 0
	v_writelane_b32 v253, s13, 49
	s_add_u32 s12, s8, 0x3400
	s_addc_u32 s13, s9, 0
	v_writelane_b32 v253, s12, 50
	s_nop 1
	v_writelane_b32 v253, s13, 51
	s_add_u32 s12, s8, 0x3500
	s_addc_u32 s13, s9, 0
	v_writelane_b32 v253, s12, 52
	s_cmp_lt_i32 s22, 0
	s_nop 0
	v_writelane_b32 v253, s13, 53
	s_mul_i32 s12, s22, 33
	s_cselect_b32 s3, s12, s3
	s_add_i32 s3, s3, s21
	s_ashr_i32 s12, s3, 31
	s_lshr_b32 s12, s12, 27
	s_add_i32 s12, s3, s12
	s_and_b32 s13, s12, 0xffe0
	s_sub_i32 s3, s3, s13
	s_bfe_i32 s13, s3, 0x80000
	s_bfe_u32 s13, s13, 0x3000c
	s_add_i32 s13, s3, s13
	s_and_b32 s14, s13, 0xf8
	s_sub_i32 s3, s3, s14
	s_ashr_i32 s12, s12, 5
	s_lshl_b32 s12, s12, 3
	s_sext_i32_i8 s3, s3
	s_add_i32 s3, s12, s3
	v_writelane_b32 v253, s3, 54
	s_bfe_i32 s3, s13, 0x80000
	s_sext_i32_i16 s3, s3
	s_ashr_i32 s3, s3, 3
	v_writelane_b32 v253, s3, 55
	s_cmp_lt_i32 s22, 4
	s_mul_i32 s3, s22, 0x62
	s_cselect_b32 s3, s3, s17
	s_add_i32 s3, s3, s21
	s_mul_hi_i32 s12, s3, 0x2aaaaaab
	s_lshr_b32 s13, s12, 31
	s_ashr_i32 s12, s12, 4
	s_add_i32 s12, s12, s13
	s_mul_i32 s13, s12, 0x60
	s_lshl_b32 s12, s12, 3
	s_sub_i32 s13, s3, s13
	s_sub_i32 s3, 0x41, s12
	s_min_u32 s14, s3, 8
	v_cvt_f32_ubyte0_e32 v2, s14
	v_writelane_b32 v253, s22, 56
	v_cvt_f32_i32_e32 v1, s13
	v_rcp_iflag_f32_e32 v3, v2
	v_writelane_b32 v253, s21, 57
	s_bfe_i32 s3, s15, 0x10017
	v_writelane_b32 v253, s3, 58
	s_abs_i32 s3, s16
	v_writelane_b32 v253, s3, 59
	s_xor_b32 s3, s16, 0xffffff00
	s_max_i32 s3, s2, s3
	v_mul_f32_e32 v3, v1, v3
	v_writelane_b32 v253, s3, 60
	s_ashr_i32 s2, s2, 31
	v_trunc_f32_e32 v3, v3
	v_writelane_b32 v253, s2, 61
	s_ashr_i32 s2, s13, 30
	v_fma_f32 v1, -v3, v2, v1
	s_or_b32 s15, s2, 1
	v_cmp_ge_f32_e64 s[2:3], |v1|, v2
	s_and_b64 s[2:3], s[2:3], exec
	v_lshrrev_b32_e32 v1, 20, v0
	v_lshrrev_b32_e32 v0, 10, v0
	s_load_dword s3, s[0:1], 0xc8
	v_or_b32_e32 v0, v0, v1
	v_cvt_i32_f32_e32 v1, v3
	s_movk_i32 s2, 0x3ff
	v_and_or_b32 v0, v0, s2, v202
	s_mul_i32 s2, s19, s18
	s_waitcnt lgkmcnt(0)
	s_mul_i32 s49, s2, s3
	s_cselect_b32 s2, s15, 0
	v_readfirstlane_b32 s3, v1
	s_add_i32 s2, s3, s2
	s_mul_i32 s3, s2, s14
	s_sub_i32 s3, s13, s3
	s_sext_i32_i8 s3, s3
	s_add_i32 s3, s12, s3
	v_writelane_b32 v253, s3, 62
	s_sext_i32_i8 s2, s2
	v_writelane_b32 v253, s2, 63
	s_lshl_b32 s2, s18, 4
	v_writelane_b32 v254, s2, 0
	s_lshl_b32 s2, s93, 8
	s_ashr_i32 s97, s96, 31
	v_writelane_b32 v254, s2, 1
	s_lshl_b32 s2, s18, 8
	v_writelane_b32 v254, s2, 2
	s_lshl_b64 s[12:13], s[96:97], 12
	s_mul_i32 s2, s23, 0x744
	v_writelane_b32 v254, s12, 3
	s_add_u32 s2, s64, s2
	v_mov_b32_e32 v1, 0
	v_writelane_b32 v254, s13, 4
	v_writelane_b32 v254, s2, 5
	v_writelane_b32 v254, s23, 6
	v_writelane_b32 v254, s60, 7
	s_mul_hi_i32 s2, s23, 0x744
	s_addc_u32 s2, s65, s2
	v_writelane_b32 v254, s61, 8
	v_writelane_b32 v254, s62, 9
	v_writelane_b32 v254, s63, 10
	v_writelane_b32 v254, s64, 11
	v_writelane_b32 v254, s65, 12
	v_writelane_b32 v254, s66, 13
	v_writelane_b32 v254, s67, 14
	v_writelane_b32 v254, s68, 15
	v_writelane_b32 v254, s69, 16
	v_writelane_b32 v254, s70, 17
	v_writelane_b32 v254, s71, 18
	v_writelane_b32 v254, s72, 19
	v_writelane_b32 v254, s73, 20
	v_writelane_b32 v254, s74, 21
	v_writelane_b32 v254, s75, 22
	v_writelane_b32 v254, s2, 23
	s_mul_i32 s2, s18, 6
	s_add_i32 s2, s2, s20
	s_cmp_eq_u32 s18, 0x100
	s_cselect_b32 s3, 72, 0
	s_sub_i32 s2, s2, s3
	s_add_i32 s3, s2, 0xfffff9e8
	v_writelane_b32 v254, s3, 24
	s_addk_i32 s2, 0xfdc8
	v_writelane_b32 v254, s2, 25
	s_mul_i32 s2, s18, 24
	v_writelane_b32 v254, s2, 26
	s_add_i32 s2, s96, 0xffffe7a0
	s_cmp_eq_u32 s18, 0x100
	s_cselect_b32 s3, 0x120, 0
	s_sub_i32 s2, s2, s3
	v_writelane_b32 v254, s2, 27
	s_add_i32 s2, s56, 0xfffe7a00
	s_cmp_eq_u32 s18, 0x100
	s_cselect_b32 s3, 0x1200, 0
	s_sub_i32 s2, s2, s3
	v_writelane_b32 v254, s2, 28
	s_movk_i32 s2, 0x57f
	s_cmp_eq_u32 s18, 0x100
	s_cbranch_scc0 .Lcv_done
	s_movk_i32 s2, 0x4df
	s_cmp_lt_u32 s93, 48
	s_cbranch_scc0 .Lcv_done
	s_movk_i32 s2, 0x57f
	s_add_i32 s3, s20, 0x4e0
	s_nop 1
	v_writelane_b32 v254, s3, 24
	s_addk_i32 s3, 0x3e0
	s_nop 1
	v_writelane_b32 v254, s3, 25
	s_movk_i32 s3, 0x180
	s_nop 1
	v_writelane_b32 v254, s3, 27
	s_movk_i32 s3, 0x1800
	s_nop 1
	v_writelane_b32 v254, s3, 28
	s_movk_i32 s3, 0x60
	s_nop 1
	v_writelane_b32 v252, s3, 59
	s_mov_b32 s3, 0
	s_nop 1
	v_writelane_b32 v252, s3, 55
	v_writelane_b32 v252, s3, 56
	s_mov_b32 s3, -1
	s_nop 1
	v_writelane_b32 v252, s3, 57
	v_writelane_b32 v252, s3, 58
.Lcv_done:
	s_nop 1
	v_writelane_b32 v255, s2, 20
	v_writelane_b32 v254, s20, 29
	s_add_i32 s2, s20, 0x3e0
	v_writelane_b32 v254, s2, 30
	s_lshl_b32 s2, s18, 7
	v_writelane_b32 v254, s2, 31
	s_add_i32 s2, 0, 0x820
	v_writelane_b32 v254, s2, 32
	s_add_i32 s2, 0, 0x5140
	v_writelane_b32 v254, s2, 33
	s_add_i32 s2, 0, 0x20800
	v_writelane_b32 v254, s2, 34
	s_add_i32 s2, 0, 0x201b0
	v_writelane_b32 v254, s2, 35
	s_add_i32 s2, 0, 0x21000
	v_writelane_b32 v254, s2, 36
	s_add_i32 s2, 0, 0x21004
	v_writelane_b32 v254, s2, 37
	s_mov_b32 s3, 0
	s_load_dwordx16 s[60:75], s[0:1], 0x0
	v_writelane_b32 v254, s2, 38
	s_mov_b32 s0, s96
	v_mbcnt_lo_u32_b32 v2, -1, 0
	v_writelane_b32 v254, s3, 39
	v_cmp_eq_u32_e64 s[2:3], 0, v0
	v_mbcnt_hi_u32_b32 v207, -1, v2
	v_and_b32_e32 v2, 64, v207
	v_writelane_b32 v254, s2, 40
	v_add_u32_e32 v208, 64, v2
	v_xor_b32_e32 v209, 32, v207
	v_writelane_b32 v254, s3, 41
	s_waitcnt lgkmcnt(0)
	v_writelane_b32 v254, s60, 42
	v_xor_b32_e32 v210, 16, v207
	v_xor_b32_e32 v211, 8, v207
	v_writelane_b32 v254, s61, 43
	v_writelane_b32 v254, s62, 44
	v_writelane_b32 v254, s63, 45
	v_writelane_b32 v254, s64, 46
	v_writelane_b32 v254, s65, 47
	v_writelane_b32 v254, s66, 48
	v_writelane_b32 v254, s67, 49
	v_writelane_b32 v254, s68, 50
	v_writelane_b32 v254, s69, 51
	v_writelane_b32 v254, s70, 52
	v_writelane_b32 v254, s71, 53
	v_writelane_b32 v254, s72, 54
	v_writelane_b32 v254, s73, 55
	v_writelane_b32 v254, s74, 56
	v_writelane_b32 v254, s75, 57
	v_writelane_b32 v254, s93, 58
	v_writelane_b32 v254, s84, 59
	v_xor_b32_e32 v212, 4, v207
	v_xor_b32_e32 v213, 2, v207
	v_writelane_b32 v255, s89, 0
	v_writelane_b32 v255, s90, 1
	v_writelane_b32 v255, s91, 2
	v_writelane_b32 v255, s0, 3
	v_writelane_b32 v254, s85, 60
	v_writelane_b32 v254, s86, 61
	v_writelane_b32 v255, s1, 4
	v_writelane_b32 v255, s46, 5
	v_writelane_b32 v254, s87, 62
	v_xor_b32_e32 v214, 1, v207
	v_writelane_b32 v255, s47, 6
	v_writelane_b32 v255, s48, 7
	v_writelane_b32 v255, s44, 8
	v_mov_b32_e32 v238, v1
	v_mov_b32_e32 v239, v1
	v_writelane_b32 v255, s45, 9
	v_writelane_b32 v255, s49, 10
	v_mov_b32_e32 v240, v1
	v_mov_b32_e32 v241, v1
	s_mov_b64 s[20:21], 0x80
	v_writelane_b32 v254, s88, 63
	v_writelane_b32 v255, s56, 11
	s_branch .LBB0_10

.LBB0_485:
	s_or_b64 exec, exec, s[34:35]
	v_readlane_b32 s2, v252, 59
	s_add_i32 s1, s1, s2
	v_readlane_b32 s2, v254, 27
	v_readlane_b32 s3, v255, 20
	s_cmp_gt_i32 s1, s3
	s_nop 0
	v_add_u32_e32 v26, s2, v26
	v_readlane_b32 s2, v254, 28
	s_nop 1
	v_add_u32_e32 v27, s2, v27
	s_cbranch_scc1 .LBB0_498
